# even-mixer conv section: thread->(part,channel,token) remap so each wave holds one of q/k/v parts (removes 3-way divergent execution)
# speedup vs baseline: 1.0536x; 1.0148x over previous
; __device__ __forceinline__ void phase_even_mix(const int wid_s, CParams& p, int j, LAS unsigned char* lds) {
;     ...
;                 if (tid < 384) {
;                     const int gq = tid % 48, part = gq >> 4, c8 = (gq & 15) * 8, tok8 = (tid / 48) * 8;
;                     float wv[4][8];
; #pragma unroll
;                     for (int jj = 0; jj < 4; ++jj)
; #pragma unroll
;                         for (int e = 0; e < 8; ++e) wv[jj][e] = cw[jj * 1536 + part * 512 + h * 128 + c8 + e];
;                     const h16* xp = proj + (size_t)tc0 * EV_N + 1024 + part * 512 + h * 128 + c8;
;                     const float glast = pass ? gcs[63] : 0.f;
;                     h16x8 xa[11];
; #pragma unroll
;                     for (int r = 0; r < 11; ++r) { const int tt = tok8 - 3 + r; const bool okr = tin + tt >= 0;
;                         xa[r] = *(const h16x8*)(xp + (long)(okr ? tt : 0) * EV_N);
;                         if (!okr) {
; #pragma unroll
;                             for (int e = 0; e < 8; ++e) xa[r][e] = (h16)0.f; } }
.LBB0_1064:
	v_mov_b32_e32 v154, v153
	s_movk_i32 s6, 0x80
	s_nop 0
	v_cmp_gt_i32_e32 vcc, s6, v154
	s_and_saveexec_b64 s[6:7], vcc
	v_lshl_add_u32 v0, v154, 2, 0
	v_add_u32_e32 v0, 0x23400, v0
	ds_write_b32 v0, v1
	s_or_b64 exec, exec, s[6:7]
	s_xor_b64 s[84:85], s[4:5], -1
	v_readlane_b32 s4, v252, 43
	s_or_b32 s64, s12, s4
	s_ashr_i32 s4, s64, 4
	v_readlane_b32 s5, v252, 19
	s_or_b32 s90, s4, s5
	s_movk_i32 s4, 0x17f
	v_add_u32_e32 v0, 0xfffffe80, v154
	v_cmp_lt_i32_e64 s[6:7], s4, v154
	s_movk_i32 s4, 0x1c0
	v_add_u32_e32 v2, s64, v0
	v_cmp_gt_u32_e64 s[8:9], s4, v154
	v_ashrrev_i32_e32 v3, 31, v2
	v_readlane_b32 s4, v252, 47
	v_lshlrev_b64 v[2:3], 5, v[2:3]
	v_readlane_b32 s5, v252, 48
	s_ashr_i32 s91, s90, 31
	v_readlane_b32 s13, v252, 30
	v_lshl_add_u64 v[78:79], s[4:5], 0, v[2:3]
	v_lshlrev_b32_e32 v2, 2, v0
	v_readlane_b32 s4, v252, 5
	v_cmp_eq_u32_e64 s[10:11], 63, v0
	s_movk_i32 s54, 0x1a00
	v_add_u32_e32 v155, s4, v2
	v_readlane_b32 s4, v252, 6
	s_movk_i32 s82, 0x48
	s_waitcnt lgkmcnt(0)
	v_add_u32_e32 v162, s4, v2
	s_lshl_b64 s[4:5], s[90:91], 2
	s_add_u32 s92, s13, s4
	v_readlane_b32 s4, v252, 31
	s_addc_u32 s93, s4, s5
	v_lshrrev_b32_e32 v4, 6, v154
	v_cmp_lt_u32_e32 vcc, 2, v4
	v_and_b32_e32 v6, 63, v154
	v_cndmask_b32_e64 v5, 0, 1, vcc
	v_mul_u32_u24_e32 v7, 3, v5
	v_lshl_or_b32 v6, v5, 6, v6
	v_sub_u32_e32 v4, v4, v7
	v_lshrrev_b32_e32 v7, 4, v6
	v_and_b32_e32 v6, 15, v6
	v_mul_u32_u24_e32 v7, 48, v7
	v_lshl_add_u32 v6, v4, 4, v6
	v_add_u32_e32 v8, v7, v6
	s_mov_b32 s4, 0x2aaaaaab
	v_mul_hi_i32 v0, v8, s4
	v_lshrrev_b32_e32 v2, 31, v0
	v_ashrrev_i32_e32 v0, 3, v0
	v_add_u32_e32 v0, v0, v2
	v_mul_lo_u32 v2, v0, 48
	v_sub_u32_e32 v5, v8, v2
	v_ashrrev_i32_e32 v6, 4, v5
	v_lshlrev_b32_e32 v2, 3, v5
	s_mul_i32 s4, s64, 0x1a00
	v_and_b32_e32 v7, 0x78, v2
	v_lshlrev_b32_e32 v2, 9, v6
	s_mul_hi_i32 s5, s64, 0x1a00
	s_add_u32 s4, s86, s4
	s_addc_u32 s5, s87, s5
	v_ashrrev_i32_e32 v3, 31, v2
	v_or3_b32 v4, v2, s83, v7
	v_lshl_add_u64 v[2:3], v[2:3], 1, s[4:5]
	v_readlane_b32 s4, v252, 46
	s_nor_b32 s52, s12, s4
	v_readlane_b32 s4, v252, 49
	v_lshlrev_b32_e32 v163, 3, v0
	v_lshlrev_b32_e32 v0, 1, v7
	v_readlane_b32 s5, v252, 50
	v_cmp_lt_u32_e64 s[12:13], 15, v5
	v_ashrrev_i32_e32 v5, 31, v4
	v_lshl_add_u64 v[80:81], s[4:5], 0, v[0:1]
	s_movk_i32 s4, 0x180
	v_cmp_eq_u32_e64 s[18:19], s4, v154
	s_movk_i32 s4, 0x182
	v_cmp_gt_u32_e64 s[20:21], s4, v154
	s_movk_i32 s4, 0x184
	v_cmp_gt_u32_e64 s[22:23], s4, v154
	s_movk_i32 s4, 0x188
	v_cmp_gt_u32_e64 s[24:25], s4, v154
	s_movk_i32 s4, 0x190
	v_cmp_gt_u32_e64 s[26:27], s4, v154
	s_movk_i32 s4, 0x1a0
	v_cmp_gt_u32_e64 s[28:29], s4, v154
	v_readlane_b32 s4, v252, 36
	v_readlane_b32 s5, v252, 37
	v_add_u32_e32 v8, -3, v163
	v_lshl_add_u64 v[2:3], v[2:3], 0, s[58:59]
	v_lshl_add_u64 v[82:83], v[4:5], 2, s[4:5]
	s_mov_b64 s[4:5], 0x1800
	v_lshl_add_u64 v[84:85], v[82:83], 0, s[4:5]
	s_mov_b64 s[4:5], 0x3000
	v_cmp_lt_i32_e64 s[30:31], s52, v8
	v_lshl_add_u64 v[2:3], v[2:3], 0, v[0:1]
	v_add_u32_e32 v76, 0, v0
	v_lshl_add_u64 v[86:87], v[82:83], 0, s[4:5]
	s_mov_b64 s[4:5], 0x4800
	v_cndmask_b32_e64 v0, 0, v8, s[30:31]
	v_lshl_add_u64 v[88:89], v[82:83], 0, s[4:5]
	v_mad_i64_i32 v[90:91], s[4:5], v0, s54, v[2:3]
	v_add_u32_e32 v0, -2, v163
	v_cmp_lt_i32_e64 s[34:35], s52, v0
	v_cmp_lt_i32_e64 s[38:39], s52, v163
	v_cmp_gt_i32_e64 s[40:41], s52, v163
	v_cndmask_b32_e64 v0, 0, v0, s[34:35]
	v_mad_i64_i32 v[92:93], s[4:5], v0, s54, v[2:3]
	v_add_u32_e32 v0, -1, v163
	v_cmp_lt_i32_e64 s[36:37], s52, v0
	s_add_i32 s65, 0, 0x23400
	v_cmp_ne_u32_e64 s[14:15], 1, v6
	v_cndmask_b32_e64 v0, 0, v0, s[36:37]
	v_mad_i64_i32 v[94:95], s[4:5], v0, s54, v[2:3]
	v_cndmask_b32_e64 v0, 0, v163, s[38:39]
	v_mad_i64_i32 v[96:97], s[4:5], v0, s54, v[2:3]
	v_or_b32_e32 v0, 1, v163
	v_cndmask_b32_e64 v0, v0, 0, s[40:41]
	v_mad_i64_i32 v[98:99], s[4:5], v0, s54, v[2:3]
	v_or_b32_e32 v0, 2, v163
	v_cmp_lt_i32_e64 s[42:43], s52, v0
	v_cmp_gt_i32_e64 s[16:17], 2, v6
	v_lshl_add_u32 v164, v6, 8, s65
	v_cndmask_b32_e64 v0, 0, v0, s[42:43]
	v_mad_i64_i32 v[100:101], s[4:5], v0, s54, v[2:3]
	v_or_b32_e32 v0, 3, v163
	v_cmp_lt_i32_e64 s[44:45], s52, v0
	v_mul_u32_u24_e32 v165, 0x48, v7
	s_barrier
	v_cndmask_b32_e64 v0, 0, v0, s[44:45]
	v_mad_i64_i32 v[102:103], s[4:5], v0, s54, v[2:3]
	v_or_b32_e32 v0, 4, v163
	v_cmp_lt_i32_e64 s[46:47], s52, v0
	s_nop 1
	v_cndmask_b32_e64 v0, 0, v0, s[46:47]
	v_mad_i64_i32 v[104:105], s[4:5], v0, s54, v[2:3]
	v_or_b32_e32 v0, 5, v163
	v_cmp_lt_i32_e64 s[48:49], s52, v0
	s_nop 1
	v_cndmask_b32_e64 v0, 0, v0, s[48:49]
	v_mad_i64_i32 v[106:107], s[4:5], v0, s54, v[2:3]
	v_or_b32_e32 v0, 6, v163
	v_cmp_lt_i32_e64 s[50:51], s52, v0
	s_nop 1
	v_cndmask_b32_e64 v0, 0, v0, s[50:51]
	v_mad_i64_i32 v[108:109], s[4:5], v0, s54, v[2:3]
	v_or_b32_e32 v0, 7, v163
	v_cmp_lt_i32_e64 s[52:53], s52, v0
	s_nop 1
	v_cndmask_b32_e64 v0, 0, v0, s[52:53]
	v_mad_i64_i32 v[110:111], s[4:5], v0, s54, v[2:3]
	s_movk_i32 s4, 0x48
	v_mov_b32_e32 v0, 0x90
	v_mad_u32_u24 v167, v7, s4, v0
	v_mov_b32_e32 v0, 0xd8
	v_mad_u32_u24 v168, v7, s4, v0
	v_mov_b32_e32 v0, 0x120
	v_mad_u32_u24 v169, v7, s4, v0
	v_mov_b32_e32 v0, 0x168
	v_mad_u32_u24 v170, v7, s4, v0
	v_mov_b32_e32 v0, 0x1b0
	v_mad_u32_u24 v171, v7, s4, v0
	v_mov_b32_e32 v0, 0x1f8
	v_mad_u32_u24 v166, v7, s4, s4
	v_mad_u32_u24 v172, v7, s4, v0
	v_readlane_b32 s4, v252, 7
	s_mov_b64 s[54:55], -1
	s_nop 0
	v_mov_b32_e32 v0, s4
	v_mad_u32_u24 v173, v7, s60, v0
	s_branch .LBB0_1068
